# grid barrier: this CU's L1 invalidate issued at arrival (before the arrival atomic and the poll) instead of after the release is observed
# speedup vs baseline: 1.0146x; 1.0066x over previous
.LBB0_605:
	s_waitcnt vmcnt(0)
	s_waitcnt vmcnt(0) lgkmcnt(0)
	s_barrier
	s_and_saveexec_b64 s[4:5], s[88:89]
	v_readlane_b32 s22, v249, 57
	v_readlane_b32 s24, v249, 59
	v_readlane_b32 s26, v249, 61
	v_readlane_b32 s28, v249, 63
	v_readlane_b32 s30, v248, 1
	v_readlane_b32 s34, v248, 3
	v_readlane_b32 s36, v248, 5
	v_readlane_b32 s23, v249, 58
	v_readlane_b32 s25, v249, 60
	v_readlane_b32 s27, v249, 62
	v_readlane_b32 s29, v248, 0
	v_readlane_b32 s31, v248, 2
	v_readlane_b32 s35, v248, 4
	v_readlane_b32 s37, v248, 6
	v_readlane_b32 s21, v248, 7
	s_cbranch_execz .LBB0_133
	buffer_inv sc1
	v_readlane_b32 s6, v249, 50
	s_waitcnt vmcnt(0) expcnt(0) lgkmcnt(0)
	s_nop 0
	v_mov_b32_e32 v0, s6
	ds_read_b32 v3, v0
	v_readlane_b32 s6, v249, 51
	s_waitcnt lgkmcnt(0)
	v_cmp_ne_u32_e32 vcc, 0, v3
	v_mov_b32_e32 v0, s6
	ds_read_b32 v2, v0
	s_cbranch_vccnz .LBB0_621
	s_mov_b32 s12, 1
	s_branch .LBB0_609
